# scan loop diet: pending-output flush at the loop top reading the live accumulator (no per-step copy), six split multiplies re-packed, four per-step register copies dropped
# baseline (speedup 1.0000x reference)
; DI int tidx() { int t = threadIdx.x; asm volatile("" : "+v"(t)); return t; }
; DI void scan_item(const P& p, char* shm, int item) {
;     const int tid = tidx(), wid = __builtin_amdgcn_readfirstlane(tid >> 6);
;     const int b = item >> 6, h = (item >> 3) & 7, dir = (item >> 2) & 1, vs = item & 3;
;     const int vb = wid & 3, dh = wid >> 2;
;     const bf16_t* Q1 = (const bf16_t*)(p.ws + O_Q1);
;     const bf16_t* K1 = (const bf16_t*)(p.ws + O_K1);
;     const bf16_t* V1T = (const bf16_t*)(p.ws + O_V1T);
;     bf16_t* OX = (bf16_t*)(p.ws + (dir ? O_OB : O_OF));
;     const float logit = (dir ? p.lb : p.lf)[h];
;     const float lg2 = -log1pf(__expf(-logit)) * LOG2E;
;     const int nsteps = PB / 32;
;     auto p0_of = [&](int s) { return dir == 0 ? 32 * s : (s < 8 ? 224 - 32 * s : PB - 32 - 32 * (s - 8)); };
;     const int lane_c = tid & 63, l31_c = lane_c & 31, hh_c = lane_c >> 5;
;     const int ld_row0 = tid >> 5, ld_ch32 = tid & 31;
;     const int koff = ld_row0 * DM + ld_ch32 * 8;
;     const unsigned ldsK0 = (ld_ch32 >> 4) * 8192 + off_b(ld_row0, ld_ch32 & 15), ldsK1 = (ld_ch32 >> 4) * 8192 + off_b(ld_row0 + 16, ld_ch32 & 15);
;     const unsigned ldsQ0 = ld_row0 * SC_QST + ld_ch32 * 16, ldsQ1 = ldsQ0 + 16 * SC_QST;
;     const int voff = (tid >> 2) * 32 + (tid & 3) * 8;
;     const unsigned ldsV = (tid >> 2) * SC_VST + (tid & 3) * 16;
;     const unsigned xrow_c = ((l31_c & 3) << 2) | ((l31_c >> 2) & 3);
;     const unsigned Lrow = 256u * l31_c + 16u * xrow_c;
;     const unsigned Lrd_c = Lrow ^ (16u * hh_c);
;     const unsigned q4_c = (lane_c & 15) >> 2, pp_c = lane_c & 3, u_c = 2 * ((lane_c >> 4) & 1) + (pp_c >> 1);
;     const unsigned Ltr_c = 256u * (8u * hh_c + q4_c) + 8u * (pp_c & 1) + 64u * q4_c + 16u * (u_c ^ (2u * hh_c));
;     const unsigned vrow_c = (vb * 32 + l31_c) * SC_VST;
;     const unsigned qrow_c = l31_c * SC_QST + 8u * hh_c;
;     ...
;     f32x16 st[4];
; #pragma unroll
;     for (int d = 0; d < 4; ++d)
; #pragma unroll
;         for (int r = 0; r < 16; ++r) st[d][r] = 0.f;
;     f32x16 oprev;
; #pragma unroll
;     for (int r = 0; r < 16; ++r) oprev[r] = 0.f;
.LBB0_2236:
	s_lshl_b32 s3, s64, 2
	s_and_b32 s3, s3, 28
	s_and_b32 s4, s64, 0xffffffe0
	s_bfe_u32 s2, s64, 0x20003
	s_or_b32 s3, s3, s4
	s_or_b32 s4, s3, s2
	s_and_b64 s[2:3], s[0:1], exec
	v_mov_b32_e32 v3, v206
	s_cselect_b32 s14, s4, s64
	s_bfe_u32 s19, s14, 0x30003
	v_readfirstlane_b32 s18, v3
	s_lshr_b32 s29, s18, 6
	s_bfe_u32 s38, s18, 0x20006
	s_bfe_i32 s16, s14, 0x10002
	s_bitcmp0_b32 s14, 2
	s_cselect_b64 s[4:5], -1, 0
	s_bitcmp1_b32 s14, 2
	v_bfe_u32 v7, v3, 5, 1
	s_cselect_b64 s[6:7], -1, 0
	s_and_b64 s[2:3], s[4:5], exec
	v_and_b32_e32 v1, 31, v3
	v_lshlrev_b32_e32 v6, 2, v7
	s_mov_b32 s2, 0x22400000
	v_sub_u32_e32 v0, v1, v6
	v_sub_u32_e32 v2, v6, v1
	s_cselect_b32 s3, s2, 0x5800000
	s_cselect_b32 s9, s43, s45
	s_cselect_b32 s8, s42, s44
	s_lshl_b32 s2, s19, 2
	v_cndmask_b32_e64 v11, v2, v0, s[4:5]
	v_mov_b32_e32 v0, s2
	global_load_dword v2, v0, s[8:9]
	v_ashrrev_i32_e32 v24, 5, v3
	v_lshlrev_b32_e32 v4, 9, v3
	v_lshlrev_b32_e32 v8, 2, v24
	v_add_u32_e32 v12, 16, v24
	v_and_b32_e32 v5, 15, v3
	v_and_b32_e32 v4, 0x2000, v4
	v_bfe_u32 v9, v24, 2, 2
	v_and_b32_e32 v8, 12, v8
	v_lshlrev_b32_e32 v13, 2, v12
	v_lshl_add_u32 v26, v24, 8, v4
	v_lshl_add_u32 v27, v12, 8, v4
	v_bitop3_b32 v28, v8, v5, v9 bitop3:0x36
	v_and_b32_e32 v4, 12, v13
	s_mov_b32 s2, 0x3f2aaaab
	v_bitop3_b32 v29, v4, v5, v9 bitop3:0x36
	s_mov_b32 s8, 0x3f317218
	s_mov_b32 s9, 0x7f800000
	v_lshlrev_b32_e32 v166, 3, v7
	v_and_b32_e32 v10, 63, v3
	v_lshlrev_b32_e32 v25, 3, v1
	v_lshl_or_b32 v192, v29, 4, v27
	v_lshl_or_b32 v195, v28, 4, v26
	v_lshlrev_b32_e32 v191, 4, v1
	v_lshlrev_b32_e32 v31, 8, v1
	v_lshlrev_b32_e32 v178, 4, v10
	v_mov_b32_e32 v0, 0
	v_lshlrev_b32_e32 v189, 4, v7
	s_mov_b32 s86, s15
	s_mov_b32 s87, s15
	s_mov_b32 s88, s15
	v_mov_b32_e32 v64, v0
	v_mov_b32_e32 v65, v0
	v_mov_b32_e32 v66, v0
	v_mov_b32_e32 v67, v0
	v_mov_b32_e32 v68, v0
	v_mov_b32_e32 v69, v0
	v_mov_b32_e32 v70, v0
	v_mov_b32_e32 v71, v0
	v_mov_b32_e32 v72, v0
	v_mov_b32_e32 v73, v0
	v_mov_b32_e32 v74, v0
	v_mov_b32_e32 v75, v0
	v_mov_b32_e32 v76, v0
	v_mov_b32_e32 v77, v0
	v_mov_b32_e32 v78, v0
	v_mov_b32_e32 v79, v0
	v_mov_b32_e32 v48, v0
	v_mov_b32_e32 v49, v0
	v_mov_b32_e32 v50, v0
	v_mov_b32_e32 v51, v0
	v_mov_b32_e32 v52, v0
	v_mov_b32_e32 v53, v0
	v_mov_b32_e32 v54, v0
	v_mov_b32_e32 v55, v0
	v_mov_b32_e32 v56, v0
	v_mov_b32_e32 v57, v0
	v_mov_b32_e32 v58, v0
	v_mov_b32_e32 v59, v0
	v_mov_b32_e32 v60, v0
	v_mov_b32_e32 v61, v0
	v_mov_b32_e32 v62, v0
	v_mov_b32_e32 v63, v0
	v_mov_b32_e32 v36, v0
	v_mov_b32_e32 v37, v0
	v_mov_b32_e32 v38, v0
	v_mov_b32_e32 v39, v0
	v_mov_b32_e32 v40, v0
	v_mov_b32_e32 v41, v0
	v_mov_b32_e32 v42, v0
	v_mov_b32_e32 v43, v0
	v_mov_b32_e32 v44, v0
	v_mov_b32_e32 v45, v0
	v_mov_b32_e32 v46, v0
	v_mov_b32_e32 v47, v0
	v_mov_b32_e32 v26, v0
	v_mov_b32_e32 v28, v0
	s_waitcnt vmcnt(0)
	v_mul_f32_e32 v2, 0xbfb8aa3b, v2
	v_exp_f32_e32 v2, v2
	s_nop 0
	v_add_f32_e32 v8, 1.0, v2
	v_add_f32_e32 v9, -1.0, v8
	v_frexp_mant_f32_e32 v12, v8
	v_cvt_f64_f32_e32 v[4:5], v8
	v_sub_f32_e32 v13, v9, v8
	v_frexp_exp_i32_f64_e32 v4, v[4:5]
	v_cmp_gt_f32_e32 vcc, s2, v12
	v_sub_f32_e32 v9, v2, v9
	v_add_f32_e32 v5, 1.0, v13
	v_subbrev_co_u32_e32 v4, vcc, 0, v4, vcc
	v_add_f32_e32 v5, v9, v5
	v_sub_u32_e32 v9, 0, v4
	v_ldexp_f32 v8, v8, v9
	v_add_f32_e32 v12, -1.0, v8
	v_add_f32_e32 v13, 1.0, v8
	v_ldexp_f32 v5, v5, v9
	v_add_f32_e32 v9, 1.0, v12
	v_add_f32_e32 v14, -1.0, v13
	v_sub_f32_e32 v9, v8, v9
	v_sub_f32_e32 v8, v8, v14
	v_add_f32_e32 v14, v5, v9
	v_add_f32_e32 v5, v5, v8
	v_add_f32_e32 v16, v13, v5
	v_rcp_f32_e32 v17, v16
	v_add_f32_e32 v9, v12, v14
	v_sub_f32_e32 v12, v9, v12
	v_sub_f32_e32 v8, v16, v13
	v_mul_f32_e32 v19, v9, v17
	v_sub_f32_e32 v18, v14, v12
	v_mul_f32_e32 v12, v16, v19
	v_sub_f32_e32 v5, v5, v8
	v_fma_f32 v14, v19, v16, -v12
	v_fmac_f32_e32 v14, v19, v5
	v_add_f32_e32 v8, v12, v14
	v_sub_f32_e32 v13, v9, v8
	v_mov_b32_e32 v15, v8
	v_pk_add_f32 v[8:9], v[8:9], v[12:13] neg_lo:[0,1] neg_hi:[0,1]
	v_cvt_f32_i32_e32 v4, v4
	v_pk_add_f32 v[8:9], v[8:9], v[14:15] neg_lo:[0,1] neg_hi:[0,1]
	v_cmp_neq_f32_e32 vcc, s9, v2
	v_add_f32_e32 v9, v18, v9
	v_add_f32_e32 v8, v8, v9
	v_add_f32_e32 v9, v13, v8
	v_mul_f32_e32 v15, v17, v9
	v_mul_f32_e32 v12, v16, v15
	v_sub_f32_e32 v13, v13, v9
	v_add_f32_e32 v20, v19, v15
	v_fma_f32 v14, v15, v16, -v12
	v_add_f32_e32 v18, v8, v13
	v_sub_f32_e32 v8, v20, v19
	v_fmac_f32_e32 v14, v15, v5
	v_sub_f32_e32 v5, v15, v8
	v_add_f32_e32 v8, v12, v14
	v_sub_f32_e32 v13, v9, v8
	v_mov_b32_e32 v15, v8
	v_pk_add_f32 v[8:9], v[8:9], v[12:13] neg_lo:[0,1] neg_hi:[0,1]
	s_mov_b32 s2, 0x33800000
	v_pk_add_f32 v[8:9], v[8:9], v[14:15] neg_lo:[0,1] neg_hi:[0,1]
	s_nop 0
	v_add_f32_e32 v9, v18, v9
	v_add_f32_e32 v8, v8, v9
	v_add_f32_e32 v8, v13, v8
	v_mul_f32_e32 v8, v17, v8
	v_add_f32_e32 v5, v5, v8
	v_add_f32_e32 v8, v20, v5
	v_mul_f32_e32 v12, v8, v8
	v_sub_f32_e32 v13, v8, v20
	v_fmamk_f32 v14, v12, 0x3e9b6dac, v162
	v_sub_f32_e32 v13, v5, v13
	v_mul_f32_e32 v5, v8, v12
	v_fmaak_f32 v133, v12, v14, 0x3f2aaada
	v_ldexp_f32 v15, v13, 1
	v_pk_mul_f32 v[12:13], v[4:5], v[132:133]
	v_ldexp_f32 v9, v8, 1
	v_fma_f32 v8, v4, s8, -v12
	v_fmac_f32_e32 v8, 0xb102e308, v4
	v_pk_add_f32 v[4:5], v[12:13], v[8:9]
	v_mov_b32_e32 v14, v12
	v_sub_f32_e32 v18, v5, v9
	v_pk_add_f32 v[16:17], v[4:5], v[12:13] neg_lo:[0,1] neg_hi:[0,1]
	v_sub_f32_e32 v13, v13, v18
	v_add_f32_e32 v15, v15, v13
	v_pk_add_f32 v[20:21], v[4:5], v[14:15]
	v_mov_b32_e32 v9, v4
	v_mov_b32_e32 v17, v21
	v_pk_add_f32 v[22:23], v[8:9], v[16:17] neg_lo:[0,1] neg_hi:[0,1]
	v_pk_add_f32 v[8:9], v[8:9], v[16:17]
	v_mov_b32_e32 v12, v5
	v_mov_b32_e32 v19, v4
; DI int crow(int r, int h) { return (r & 3) + 8 * (r >> 2) + 4 * h; }
; DI void scan_item(const P& p, char* shm, int item) {
;     ...
;     auto issue_chunk = [&](int s) {
;         const int p0 = p0_of(s);
;         const bool lat = p0 >= CTXL;
;         const bf16_t* kp = K1 + ((size_t)b * PB + p0) * DM + h * 256;
;         const bf16_t* qp = Q1 + ((size_t)b * SEQ + (p0 - CTXL)) * DM + h * 256;
;         const bf16_t* vp = V1T + (((size_t)b * (PB / 32) + (p0 >> 5)) * 4096 + h * 512 + vs * 128) * 32;
;         kq[0] = *(const bf16x8*)(kp + koff);
;         kq[1] = *(const bf16x8*)(kp + koff + 16 * DM);
;         if (lat) { qq[0] = *(const bf16x8*)(qp + koff); qq[1] = *(const bf16x8*)(qp + koff + 16 * DM); }
;         vv = *(const bf16x8*)(vp + voff);
;     ...
;     float dmask[16];
;     float qlane;
;     {
; #pragma unroll
;         for (int r = 0; r < 16; ++r) {
;             const int j = crow(r, hh_c);
;             const int dd = dir == 0 ? l31_c - j : j - l31_c;
;             dmask[r] = dd >= 0 ? __builtin_amdgcn_exp2f(lg2 * (float)dd) : 0.f;
;         }
;         qlane = __builtin_amdgcn_exp2f(lg2 * (float)(dir == 0 ? 1 + 4 * hh_c : 32 - 4 * hh_c));
;     }
	v_pk_add_f32 v[4:5], v[8:9], v[4:5] op_sel:[1,0] op_sel_hi:[0,1] neg_lo:[0,1] neg_hi:[0,1]
	v_mov_b32_e32 v18, v15
	v_mov_b32_e32 v14, v21
	v_mov_b32_e32 v15, v9
	v_mov_b32_e32 v13, v4
	v_pk_add_f32 v[16:17], v[20:21], v[4:5] op_sel_hi:[1,0] neg_lo:[0,1] neg_hi:[0,1]
	v_pk_add_f32 v[4:5], v[14:15], v[12:13] neg_lo:[0,1] neg_hi:[0,1]
	v_mov_b32_e32 v16, v22
	v_pk_add_f32 v[4:5], v[18:19], v[4:5] neg_lo:[0,1] neg_hi:[0,1]
	v_mov_b32_e32 v23, v9
	v_pk_add_f32 v[12:13], v[16:17], v[4:5]
	s_ashr_i32 s8, s14, 6
	v_pk_add_f32 v[14:15], v[12:13], v[12:13] op_sel:[0,1] op_sel_hi:[1,0]
	s_mul_hi_i32 s77, s8, 0x1100
	v_pk_add_f32 v[8:9], v[8:9], v[14:15] op_sel:[1,0] op_sel_hi:[0,1]
	v_mov_b32_e32 v13, v8
	v_mov_b32_e32 v5, v14
	v_pk_add_f32 v[14:15], v[12:13], v[22:23] neg_lo:[0,1] neg_hi:[0,1]
	v_bfe_u32 v13, v3, 1, 1
	v_sub_f32_e32 v9, v12, v14
	v_pk_add_f32 v[4:5], v[4:5], v[14:15] neg_lo:[0,1] neg_hi:[0,1]
	v_sub_f32_e32 v9, v22, v9
	v_add_f32_e32 v4, v4, v9
	v_add_f32_e32 v4, v4, v5
	v_add_f32_e32 v4, v8, v4
	v_lshlrev_b32_e32 v8, 2, v3
	v_bfe_u32 v12, v3, 2, 2
	v_cndmask_b32_e32 v4, v163, v4, vcc
	v_cmp_ngt_f32_e32 vcc, -1.0, v2
	v_and_or_b32 v8, v8, 12, v12
	v_lshlrev_b32_e32 v30, 4, v8
	v_cndmask_b32_e32 v4, v164, v4, vcc
	v_cmp_neq_f32_e32 vcc, -1.0, v2
	v_lshrrev_b32_e32 v8, 3, v3
	v_and_or_b32 v8, v8, 2, v13
	v_cndmask_b32_e32 v4, v165, v4, vcc
	v_cmp_lt_f32_e64 vcc, |v2|, s2
	v_lshlrev_b32_e32 v8, 4, v8
	v_lshrrev_b32_e32 v9, 2, v3
	v_cndmask_b32_e32 v5, v4, v2, vcc
	v_lshlrev_b32_e32 v2, 3, v3
	v_lshlrev_b32_e32 v4, 4, v3
	v_or_b32_e32 v13, v166, v12
	v_and_b32_e32 v14, 8, v2
	v_bitop3_b32 v3, v8, v3, 32 bitop3:0x78
	v_mul_u32_u24_e32 v8, 0x210, v1
	v_lshlrev_b32_e32 v12, 6, v12
	v_or_b32_e32 v177, v166, v8
	v_lshl_or_b32 v8, v13, 8, v14
	v_or3_b32 v133, v8, v12, v3
	v_cvt_f32_u32_e32 v3, v11
	s_movk_i32 s2, 0x210
	v_mul_lo_u32 v190, v24, s2
	v_and_b32_e32 v4, 48, v4
	v_lshl_or_b32 v8, v24, 11, v25
	v_or_b32_e32 v24, 1, v6
	v_mul_f32_e32 v32, 0xbfb8aa3b, v5
	v_mad_u64_u32 v[104:105], s[74:75], v9, s21, v[4:5]
	v_sub_u32_e32 v4, v1, v24
	v_sub_u32_e32 v5, v24, v1
	v_mul_f32_e32 v3, v32, v3
	v_cndmask_b32_e64 v4, v5, v4, s[4:5]
	v_exp_f32_e32 v3, v3
	v_cvt_f32_u32_e32 v5, v4
	v_cmp_lt_i32_e32 vcc, -1, v11
	v_or_b32_e32 v11, 3, v6
	v_sub_u32_e32 v12, v1, v11
	v_cndmask_b32_e32 v168, 0, v3, vcc
	v_mul_f32_e32 v3, v32, v5
	v_or_b32_e32 v5, 2, v6
	v_sub_u32_e32 v9, v1, v5
	v_sub_u32_e32 v5, v5, v1
	v_cndmask_b32_e64 v5, v5, v9, s[4:5]
	v_sub_u32_e32 v11, v11, v1
	v_exp_f32_e32 v3, v3
	v_cvt_f32_u32_e32 v9, v5
	v_cndmask_b32_e64 v11, v11, v12, s[4:5]
	v_cvt_f32_u32_e32 v12, v11
	v_cmp_lt_i32_e32 vcc, -1, v4
	s_lshl_b32 s2, s38, 5
	s_add_u32 s37, s26, s3
	v_cndmask_b32_e32 v169, 0, v3, vcc
	v_mul_f32_e32 v3, v32, v9
	v_exp_f32_e32 v3, v3
	v_mul_f32_e32 v4, v32, v12
	v_or_b32_e32 v9, 8, v6
	v_exp_f32_e32 v4, v4
	v_sub_u32_e32 v12, v1, v9
	v_sub_u32_e32 v9, v9, v1
	v_cndmask_b32_e64 v9, v9, v12, s[4:5]
	v_cvt_f32_u32_e32 v12, v9
	v_cmp_lt_i32_e32 vcc, -1, v5
	s_addc_u32 s39, s27, 0
	s_and_b32 s3, s16, 0xe0
	v_cndmask_b32_e32 v170, 0, v3, vcc
	v_cmp_lt_i32_e32 vcc, -1, v11
	v_or_b32_e32 v11, 10, v6
	v_mul_f32_e32 v3, v32, v12
	v_cndmask_b32_e32 v171, 0, v4, vcc
	v_or_b32_e32 v4, 9, v6
	v_sub_u32_e32 v5, v1, v4
	v_sub_u32_e32 v4, v4, v1
	v_cndmask_b32_e64 v4, v4, v5, s[4:5]
	v_sub_u32_e32 v12, v1, v11
	v_sub_u32_e32 v11, v11, v1
	v_exp_f32_e32 v3, v3
	v_cvt_f32_u32_e32 v5, v4
	v_cndmask_b32_e64 v11, v11, v12, s[4:5]
	v_cvt_f32_u32_e32 v12, v11
	v_cmp_lt_i32_e32 vcc, -1, v9
	v_or_b32_e32 v9, 11, v6
	s_mul_i32 s78, s8, 0x1100
	v_cndmask_b32_e32 v172, 0, v3, vcc
	v_mul_f32_e32 v3, v32, v5
	v_exp_f32_e32 v3, v3
	v_mul_f32_e32 v5, v32, v12
	v_exp_f32_e32 v5, v5
	v_sub_u32_e32 v12, v1, v9
	v_sub_u32_e32 v9, v9, v1
	v_cndmask_b32_e64 v9, v9, v12, s[4:5]
	v_cvt_f32_u32_e32 v12, v9
	v_cmp_lt_i32_e32 vcc, -1, v4
	v_or_b32_e32 v4, 16, v6
	s_or_b32 s74, s78, s3
	v_cndmask_b32_e32 v173, 0, v3, vcc
	v_cmp_lt_i32_e32 vcc, -1, v11
	v_mul_f32_e32 v3, v32, v12
	v_exp_f32_e32 v3, v3
	v_cndmask_b32_e32 v174, 0, v5, vcc
	v_sub_u32_e32 v5, v1, v4
	v_sub_u32_e32 v4, v4, v1
	v_cndmask_b32_e64 v11, v4, v5, s[4:5]
	v_or_b32_e32 v5, 17, v6
	v_sub_u32_e32 v12, v1, v5
	v_sub_u32_e32 v5, v5, v1
	v_cvt_f32_u32_e32 v4, v11
	v_cndmask_b32_e64 v27, v5, v12, s[4:5]
	v_cvt_f32_u32_e32 v5, v27
	v_cmp_lt_i32_e32 vcc, -1, v9
	s_mov_b32 s75, s77
	s_ashr_i32 s36, s18, 8
	v_cndmask_b32_e32 v176, 0, v3, vcc
	v_mul_f32_e32 v3, v32, v4
	s_ashr_i32 s9, s8, 31
	s_lshl_b64 s[74:75], s[74:75], 12
	v_exp_f32_e32 v29, v3
	v_mul_f32_e32 v3, v32, v5
	s_add_u32 s17, s33, s74
	v_exp_f32_e32 v33, v3
	v_or_b32_e32 v3, 18, v6
	s_addc_u32 s28, s84, s75
	s_lshl_b32 s3, s19, 9
	v_sub_u32_e32 v4, v1, v3
	v_sub_u32_e32 v3, v3, v1
	s_add_u32 s74, s17, s3
	v_ashrrev_i32_e32 v9, 31, v8
	v_cndmask_b32_e64 v34, v3, v4, s[4:5]
	s_addc_u32 s75, s28, 0
	v_lshlrev_b64 v[4:5], 1, v[8:9]
	v_lshl_add_u64 v[8:9], s[74:75], 0, v[4:5]
	v_add_co_u32_e32 v16, vcc, s23, v8
	v_or_b32_e32 v15, s2, v1
	s_nop 0
	v_addc_co_u32_e32 v17, vcc, 0, v9, vcc
	v_mul_u32_u24_e32 v167, 0x50, v15
	global_load_dwordx4 v[12:15], v[8:9], off
	s_nop 0
	global_load_dwordx4 v[16:19], v[16:17], off
	s_lshl_b32 s14, s14, 7
	s_mul_hi_i32 s79, s8, 0x88
	s_mul_i32 s82, s8, 0x88
	s_and_b32 s16, s16, 7
	s_and_b32 s28, s14, 0x180
	s_or_b32 s16, s82, s16
	s_mov_b32 s17, s79
	s_or_b32 s14, s3, s28
	s_lshl_b64 s[74:75], s[16:17], 18
	s_lshl_b32 s16, s14, 6
	s_or_b32 s17, s74, s16
	s_add_u32 s74, s12, s17
	v_ashrrev_i32_e32 v3, 31, v2
	s_addc_u32 s75, s13, s75
	v_lshlrev_b64 v[8:9], 1, v[2:3]
	v_lshl_add_u64 v[20:21], s[74:75], 0, v[8:9]
; DI float bf2f(unsigned short b) { return __uint_as_float(((unsigned)b) << 16); }
; DI void scan_item(const P& p, char* shm, int item) {
;     ...
;     auto store_chunk = [&](int s) {
;         char* buf = shm + (s & 1) * SC_BUF;
;         const bool lat = p0_of(s) >= CTXL;
;         *(bf16x8*)(buf + SC_K + ldsK0) = kq[0];
;         *(bf16x8*)(buf + SC_K + ldsK1) = kq[1];
;         if (lat) { *(bf16x8*)(buf + SC_Q + ldsQ0) = qq[0]; *(bf16x8*)(buf + SC_Q + ldsQ1) = qq[1]; }
;         *(bf16x8*)(buf + SC_V + ldsV) = vv;
;         float f[8];
; #pragma unroll
;         for (int e = 0; e < 8; ++e) {
;             const int j = (tid & 3) * 8 + e;
;             f[e] = bf2f((unsigned short)vv[e]) * __builtin_amdgcn_exp2f(lg2 * (float)(dir == 0 ? 31 - j : j));
;         }
;         *(bf16x8*)(buf + SC_VS + ldsV) = pack8(f[0], f[1], f[2], f[3], f[4], f[5], f[6], f[7]);
;     };
;     ...
;     issue_chunk(0); store_chunk(0); issue_chunk(1);
	global_load_dwordx4 v[20:23], v[20:21], off
	v_cvt_f32_u32_e32 v35, v34
	v_cmp_lt_i32_e32 vcc, -1, v11
	v_or_b32_e32 v11, 19, v6
	s_and_b64 s[74:75], s[4:5], exec
	v_cndmask_b32_e32 v182, 0, v29, vcc
	v_cmp_lt_i32_e32 vcc, -1, v27
	v_or_b32_e32 v29, 24, v6
	v_sub_u32_e32 v27, v1, v11
	v_cndmask_b32_e32 v183, 0, v33, vcc
	v_sub_u32_e32 v11, v11, v1
	v_sub_u32_e32 v33, v1, v29
	v_sub_u32_e32 v29, v29, v1
	v_mul_f32_e32 v3, v32, v35
	v_cndmask_b32_e64 v11, v11, v27, s[4:5]
	v_cndmask_b32_e64 v29, v29, v33, s[4:5]
	v_exp_f32_e32 v3, v3
	v_cvt_f32_u32_e32 v27, v11
	v_cvt_f32_u32_e32 v33, v29
	v_cmp_lt_i32_e32 vcc, -1, v34
	s_cselect_b32 s17, 32, 0xc0
	s_or_b32 s74, s78, s17
	v_cndmask_b32_e32 v186, 0, v3, vcc
	v_mul_f32_e32 v3, v32, v27
	v_mul_f32_e32 v27, v32, v33
	v_or_b32_e32 v33, 25, v6
	v_exp_f32_e32 v3, v3
	v_sub_u32_e32 v34, v1, v33
	v_sub_u32_e32 v33, v33, v1
	v_exp_f32_e32 v27, v27
	v_cndmask_b32_e64 v33, v33, v34, s[4:5]
	v_cvt_f32_u32_e32 v34, v33
	v_cmp_lt_i32_e32 vcc, -1, v11
	v_or_b32_e32 v11, 26, v6
	s_mov_b32 s75, s77
	v_cndmask_b32_e32 v184, 0, v3, vcc
	v_cmp_lt_i32_e32 vcc, -1, v29
	v_mul_f32_e32 v3, v32, v34
	v_exp_f32_e32 v3, v3
	v_cndmask_b32_e32 v185, 0, v27, vcc
	v_sub_u32_e32 v27, v1, v11
	v_sub_u32_e32 v11, v11, v1
	v_cndmask_b32_e64 v11, v11, v27, s[4:5]
	v_cvt_f32_u32_e32 v27, v11
	v_cmp_lt_i32_e32 vcc, -1, v33
	s_lshl_b64 s[74:75], s[74:75], 12
	s_add_u32 s65, s33, s74
	v_cndmask_b32_e32 v180, 0, v3, vcc
	v_mul_f32_e32 v3, v32, v27
	v_exp_f32_e32 v3, v3
	v_cmp_lt_i32_e32 vcc, -1, v11
	v_add_u32_e32 v11, 16, v195
	s_addc_u32 s75, s84, s75
	v_cndmask_b32_e32 v181, 0, v3, vcc
	v_and_b32_e32 v3, 24, v2
	v_or_b32_e32 v29, 27, v6
	s_add_u32 s74, s65, s3
	v_sub_u32_e32 v34, v1, v29
	v_sub_u32_e32 v29, v29, v1
	s_addc_u32 s75, s75, 0
	v_cndmask_b32_e64 v29, v29, v34, s[4:5]
	v_add_u32_e32 v194, 16, v104
	s_waitcnt vmcnt(2)
	ds_write_b128 v11, v[12:15] offset:16896
	v_add_u32_e32 v11, 16, v192
	s_waitcnt vmcnt(1)
	ds_write_b128 v11, v[16:19] offset:16896
	v_bitop3_b32 v11, v2, 31, 24 bitop3:0x6c
	v_cndmask_b32_e64 v11, v3, v11, s[4:5]
	v_cvt_f32_ubyte0_e32 v11, v11
	v_mul_f32_e32 v11, v32, v11
	v_exp_f32_e32 v154, v11
	v_or_b32_e32 v11, 1, v3
	v_bitop3_b32 v12, v2, 30, 24 bitop3:0x6c
	v_cndmask_b32_e64 v11, v11, v12, s[4:5]
	v_cvt_f32_ubyte0_e32 v11, v11
	v_mul_f32_e32 v11, v32, v11
	v_exp_f32_e32 v155, v11
	v_or_b32_e32 v11, 2, v3
	v_bitop3_b32 v14, v2, 29, 24 bitop3:0x6c
	v_cndmask_b32_e64 v11, v11, v14, s[4:5]
	v_cvt_f32_ubyte0_e32 v11, v11
	v_mul_f32_e32 v11, v32, v11
	v_exp_f32_e32 v156, v11
	v_or_b32_e32 v11, 3, v3
	v_bitop3_b32 v14, v2, 28, 24 bitop3:0x6c
	v_cndmask_b32_e64 v11, v11, v14, s[4:5]
	v_cvt_f32_ubyte0_e32 v11, v11
	v_mul_f32_e32 v11, v32, v11
	v_exp_f32_e32 v157, v11
	v_or_b32_e32 v11, 4, v3
	v_bitop3_b32 v18, v2, 27, 24 bitop3:0x6c
	v_cndmask_b32_e64 v11, v11, v18, s[4:5]
	v_cvt_f32_ubyte0_e32 v11, v11
	v_mul_f32_e32 v11, v32, v11
	v_exp_f32_e32 v158, v11
	v_or_b32_e32 v11, 5, v3
	v_bitop3_b32 v18, v2, 26, 24 bitop3:0x6c
	v_cndmask_b32_e64 v11, v11, v18, s[4:5]
	v_cvt_f32_ubyte0_e32 v11, v11
	v_lshl_add_u64 v[16:17], s[74:75], 0, v[4:5]
	v_mul_f32_e32 v11, v32, v11
	v_cvt_f32_u32_e32 v34, v29
	global_load_dwordx4 v[112:115], v[16:17], off
	s_waitcnt vmcnt(1)
	ds_write_b128 v194, v[20:23] offset:33280
	v_and_b32_e32 v13, 0xffff0000, v20
	v_lshlrev_b32_e32 v12, 16, v20
	v_exp_f32_e32 v159, v11
	v_or_b32_e32 v11, 6, v3
	v_bitop3_b32 v20, v2, 25, 24 bitop3:0x6c
	v_or_b32_e32 v3, 7, v3
	v_bitop3_b32 v2, v2, 24, v2 bitop3:0xc
	v_cndmask_b32_e64 v11, v11, v20, s[4:5]
	v_cndmask_b32_e64 v2, v3, v2, s[4:5]
	v_cvt_f32_ubyte0_e32 v11, v11
	v_cvt_f32_ubyte0_e32 v2, v2
	v_mul_f32_e32 v11, v32, v11
	v_mul_f32_e32 v2, v32, v2
	v_mul_f32_e32 v27, v32, v34
	v_exp_f32_e32 v160, v11
	v_exp_f32_e32 v161, v2
	v_exp_f32_e32 v27, v27
	s_lshr_b32 s17, s17, 5
	v_and_b32_e32 v19, 0xffff0000, v22
	v_lshlrev_b32_e32 v18, 16, v22
	s_or_b32 s74, s82, s17
	s_mov_b32 s75, s79
	v_and_b32_e32 v15, 0xffff0000, v21
	v_lshlrev_b32_e32 v14, 16, v21
	v_pk_mul_f32 v[2:3], v[158:159], v[18:19]
	v_and_b32_e32 v19, 0xffff0000, v23
	v_lshlrev_b32_e32 v18, 16, v23
	s_lshl_b64 s[74:75], s[74:75], 18
	v_cmp_lt_i32_e32 vcc, -1, v29
	v_pk_mul_f32 v[12:13], v[154:155], v[12:13]
	v_pk_mul_f32 v[14:15], v[156:157], v[14:15]
	v_pk_mul_f32 v[18:19], v[160:161], v[18:19]
	s_or_b32 s16, s74, s16
	v_cndmask_b32_e32 v179, 0, v27, vcc
	v_cvt_pk_bf16_f32 v12, v12, v13
	v_cvt_pk_bf16_f32 v13, v14, v15
	v_cvt_pk_bf16_f32 v14, v2, v3
	v_cvt_pk_bf16_f32 v15, v18, v19
	v_add_co_u32_e32 v2, vcc, s23, v16
	s_add_u32 s16, s12, s16
	ds_write_b128 v194, v[12:15] offset:43520
	v_addc_co_u32_e32 v3, vcc, 0, v17, vcc
	s_addc_u32 s17, s13, s75
	v_lshl_add_u64 v[12:13], s[16:17], 0, v[8:9]
	global_load_dwordx4 v[120:123], v[2:3], off
	global_load_dwordx4 v[116:119], v[12:13], off
	s_cmpk_lt_u32 s18, 0x100
	s_cselect_b64 s[16:17], -1, 0
	s_add_u32 s74, s33, s3
	s_addc_u32 s75, s84, 0
	s_lshl_b32 s29, s29, 12
	v_lshl_add_u64 v[106:107], s[74:75], 0, v[4:5]
	s_add_i32 s65, s35, s29
	v_lshlrev_b32_e32 v2, 6, v10
	s_lshl_b64 s[74:75], s[8:9], 25
	v_add_u32_e32 v193, s65, v2
	s_add_u32 s65, s37, s74
	s_addc_u32 s74, s39, s75
	s_lshl_b32 s19, s19, 10
	s_add_u32 s19, s65, s19
	s_addc_u32 s37, s74, 0
	s_lshl_b32 s39, s28, 1
	s_add_u32 s19, s19, s39
	s_addc_u32 s37, s37, 0
	s_lshl_b32 s39, s38, 6
	s_add_u32 s75, s19, s39
	s_addc_u32 s76, s37, 0
	s_lshl_b32 s85, s36, 13
	s_and_b32 s83, s18, 0xffffff00
	s_cmp_eq_u32 s36, 1
	s_cselect_b64 s[18:19], -1, 0
	s_cmp_lg_u32 s36, 1
; DI int crow(int r, int h) { return (r & 3) + 8 * (r >> 2) + 4 * h; }
; DI void scan_item(const P& p, char* shm, int item) {
;     ...
;     const float cdec = __builtin_amdgcn_exp2f(lg2 * 32.f);
;     auto flush_prev = [&](int sprev) {
;         const float* xp = (const float*)(shm + SC_X + (sprev & 1) * 16384 + vb * 4096) + lane_c * 16;
;         bf16_t* ob = OX + ((size_t)b * SEQ + pprev) * 4096 + h * 512 + vs * 128 + vb * 32;
;         const __amdgpu_buffer_rsrc_t rs = __builtin_amdgcn_make_buffer_rsrc(ob, 0, 0x7fffffff, 0x00020000);
; #pragma unroll
;         for (int g = 0; g < 4; ++g) {
;             const f32x4 x = *(const f32x4*)(xp + 4 * g);
; #pragma unroll
;             for (int j = 0; j < 4; ++j)
;                 __builtin_amdgcn_raw_buffer_store_b16((short)(pk2(oprev[4 * g + j] + x[j], 0.f) & 0xffffu), rs, flane * 2, (j + 8 * g) * 8192, 0);
;         }
;     };
;     float dmask[16];
;     float qlane;
;     {
; #pragma unroll
;         for (int r = 0; r < 16; ++r) {
;             const int j = crow(r, hh_c);
;             const int dd = dir == 0 ? l31_c - j : j - l31_c;
;             dmask[r] = dd >= 0 ? __builtin_amdgcn_exp2f(lg2 * (float)dd) : 0.f;
;         }
;         qlane = __builtin_amdgcn_exp2f(lg2 * (float)(dir == 0 ? 1 + 4 * hh_c : 32 - 4 * hh_c));
;     }
;     const float lgs = dir == 0 ? lg2 : -lg2;
;     issue_chunk(0); store_chunk(0); issue_chunk(1);
;     __syncthreads();
;     for (int s = 0; s < nsteps; ++s) {
;         if (dh == 0 && pprev >= 0) { flush_prev(s - 1); pprev = -1; }
;         const int lane = lane_c, l31 = l31_c, hh = hh_c;
;         unsigned Lrd = Lrd_c, Ltr = Ltr_c, vrow = vrow_c, qrow = qrow_c;
;         asm volatile("" : "+v"(Lrd), "+v"(Ltr), "+v"(vrow), "+v"(qrow));
	s_cselect_b64 s[36:37], -1, 0
	s_lshl_b32 s38, s38, 12
	s_add_i32 s38, s35, s38
	s_lshl_b64 s[8:9], s[8:9], 24
	v_sub_u32_e32 v6, 32, v6
	s_add_u32 s8, s80, s8
	v_cndmask_b32_e64 v6, v6, v24, s[4:5]
	v_cndmask_b32_e64 v24, -v32, v32, s[4:5]
	v_lshlrev_b32_e32 v1, 1, v1
	s_addc_u32 s9, s81, s9
	v_lshl_or_b32 v175, v7, 15, v1
	s_add_u32 s8, s8, s3
	v_mul_f32_e32 v1, 0, v24
	v_add_u32_e32 v187, s38, v2
	s_addc_u32 s9, s9, 0
	v_exp_f32_e32 v2, v1
	v_add_f32_e32 v1, v24, v24
	v_cvt_f32_ubyte0_e32 v6, v6
	v_lshl_add_u64 v[110:111], s[8:9], 0, v[4:5]
	v_exp_f32_e32 v4, v1
	v_mul_f32_e32 v1, 0x40400000, v24
	v_mul_f32_e32 v6, v32, v6
	v_exp_f32_e32 v5, v1
	v_mul_f32_e32 v1, 0x41000000, v24
	v_exp_f32_e32 v6, v6
	v_lshl_add_u64 v[108:109], s[12:13], 0, v[8:9]
	v_exp_f32_e32 v3, v24
	v_exp_f32_e32 v8, v1
	v_mul_f32_e32 v1, 0x41100000, v24
	v_exp_f32_e32 v9, v1
	v_mul_f32_e32 v1, 0x41200000, v24
	v_exp_f32_e32 v10, v1
	v_mul_f32_e32 v1, 0x41300000, v24
	v_exp_f32_e32 v11, v1
	v_mul_f32_e32 v1, 0x41800000, v24
	v_pk_mul_f32 v[134:135], v[6:7], v[2:3] op_sel_hi:[0,1]
	v_exp_f32_e32 v2, v1
	v_mul_f32_e32 v1, 0x41880000, v24
	v_exp_f32_e32 v3, v1
	v_mul_f32_e32 v1, 0x41900000, v24
	v_pk_mul_f32 v[136:137], v[6:7], v[4:5] op_sel_hi:[0,1]
	v_exp_f32_e32 v4, v1
	v_mul_f32_e32 v1, 0x41980000, v24
	v_exp_f32_e32 v5, v1
	v_mul_f32_e32 v1, 0x41c00000, v24
	v_pk_mul_f32 v[138:139], v[6:7], v[8:9] op_sel_hi:[0,1]
	v_exp_f32_e32 v8, v1
	v_mul_f32_e32 v1, 0x41c80000, v24
	v_exp_f32_e32 v9, v1
	v_mul_f32_e32 v1, 0x41d00000, v24
	v_mul_f32_e32 v25, 0x42000000, v32
	v_pk_mul_f32 v[140:141], v[6:7], v[10:11] op_sel_hi:[0,1]
	v_exp_f32_e32 v10, v1
	v_mul_f32_e32 v1, 0x41d80000, v24
	v_exp_f32_e32 v150, v25
	v_exp_f32_e32 v11, v1
	v_bitop3_b32 v188, v30, v189, v31 bitop3:0x36
	v_pk_mul_f32 v[142:143], v[6:7], v[2:3] op_sel_hi:[0,1]
	v_mov_b32_e32 v152, v150
	v_mov_b32_e32 v153, v150
	v_pk_mul_f32 v[144:145], v[6:7], v[4:5] op_sel_hi:[0,1]
	v_pk_mul_f32 v[146:147], v[6:7], v[8:9] op_sel_hi:[0,1]
	v_pk_mul_f32 v[148:149], v[6:7], v[10:11] op_sel_hi:[0,1]
	v_mov_b32_e32 v1, v0
	v_mov_b32_e32 v2, v0
	v_mov_b32_e32 v3, v0
	v_mov_b32_e32 v4, v0
	v_mov_b32_e32 v5, v0
	v_mov_b32_e32 v6, v0
	v_mov_b32_e32 v7, v0
	v_mov_b32_e32 v8, v0
	v_mov_b32_e32 v9, v0
	v_mov_b32_e32 v10, v0
	v_mov_b32_e32 v11, v0
	v_mov_b32_e32 v12, v0
	v_mov_b32_e32 v13, v0
	v_mov_b32_e32 v14, v0
	v_mov_b32_e32 v15, v0
	s_lshl_b64 s[38:39], s[14:15], 6
	s_mov_b32 s14, s40
	v_mov_b32_e32 v32, v0
	v_mov_b32_e32 v33, v0
	v_mov_b32_e32 v34, v0
	v_mov_b32_e32 v35, v0
	v_mov_b32_e32 v16, v0
	v_mov_b32_e32 v17, v0
	v_mov_b32_e32 v18, v0
	v_mov_b32_e32 v19, v0
	v_mov_b32_e32 v20, v0
	v_mov_b32_e32 v21, v0
	v_mov_b32_e32 v22, v0
	v_mov_b32_e32 v23, v0
	v_mov_b32_e32 v24, v0
	v_mov_b32_e32 v25, v0
	v_mov_b32_e32 v27, v0
	v_mov_b32_e32 v29, v0
	v_mov_b32_e32 v30, v0
	v_mov_b32_e32 v31, v0
	s_mov_b32 s98, -1
	s_mov_b32 s99, 0
	s_waitcnt lgkmcnt(0)
	s_barrier
.LBB0_2237:
	s_cmp_gt_i32 s98, -1
	s_cselect_b64 s[8:9], -1, 0
	s_and_b64 s[8:9], s[16:17], s[8:9]
	s_andn2_b64 vcc, exec, s[8:9]
	s_cbranch_vccnz .LBB0_2239
	s_andn2_b32 s8, 0x4000, s87
	v_add_u32_e32 v88, s8, v193
	ds_read_b128 v[80:83], v88
	ds_read_b128 v[84:87], v88 offset:16
	s_lshl_b64 s[8:9], s[98:99], 13
	s_add_u32 s8, s75, s8
	s_addc_u32 s9, s76, s9
	s_waitcnt lgkmcnt(1)
	v_add_f32_e32 v80, v208, v80
	s_and_b32 s9, s9, 0xffff
	v_cvt_pk_bf16_f32 v80, v80, s0
	buffer_store_short v80, v175, s[8:11], 0 offen
	v_add_f32_e32 v80, v209, v81
	v_cvt_pk_bf16_f32 v80, v80, s0
	buffer_store_short v80, v175, s[8:11], s20 offen
	v_add_f32_e32 v80, v210, v82
	v_cvt_pk_bf16_f32 v80, v80, s0
	buffer_store_short v80, v175, s[8:11], s41 offen
	v_add_f32_e32 v80, v211, v83
	v_cvt_pk_bf16_f32 v80, v80, s0
	buffer_store_short v80, v175, s[8:11], s52 offen
	s_waitcnt lgkmcnt(0)
	v_add_f32_e32 v80, v212, v84
	v_cvt_pk_bf16_f32 v80, v80, s0
	buffer_store_short v80, v175, s[8:11], s23 offen
	v_add_f32_e32 v80, v213, v85
	v_cvt_pk_bf16_f32 v80, v80, s0
	buffer_store_short v80, v175, s[8:11], s53 offen
	v_add_f32_e32 v80, v214, v86
	v_cvt_pk_bf16_f32 v80, v80, s0
	buffer_store_short v80, v175, s[8:11], s54 offen
	ds_read_b128 v[80:83], v88 offset:32
	v_add_f32_e32 v84, v215, v87
	v_cvt_pk_bf16_f32 v84, v84, s0
	buffer_store_short v84, v175, s[8:11], s55 offen
	ds_read_b128 v[84:87], v88 offset:48
	s_waitcnt lgkmcnt(1)
	v_add_f32_e32 v80, v216, v80
	v_cvt_pk_bf16_f32 v80, v80, s0
	buffer_store_short v80, v175, s[8:11], s11 offen
	v_add_f32_e32 v80, v217, v81
	v_cvt_pk_bf16_f32 v80, v80, s0
	buffer_store_short v80, v175, s[8:11], s56 offen
	v_add_f32_e32 v80, v218, v82
	v_cvt_pk_bf16_f32 v80, v80, s0
	buffer_store_short v80, v175, s[8:11], s57 offen
	v_add_f32_e32 v80, v219, v83
	v_cvt_pk_bf16_f32 v80, v80, s0
	buffer_store_short v80, v175, s[8:11], s58 offen
	s_waitcnt lgkmcnt(0)
	v_add_f32_e32 v80, v220, v84
	v_cvt_pk_bf16_f32 v80, v80, s0
	buffer_store_short v80, v175, s[8:11], s59 offen
	v_add_f32_e32 v80, v221, v85
	v_cvt_pk_bf16_f32 v80, v80, s0
	buffer_store_short v80, v175, s[8:11], s60 offen
	v_add_f32_e32 v80, v222, v86
	v_cvt_pk_bf16_f32 v80, v80, s0
	buffer_store_short v80, v175, s[8:11], s61 offen
	v_add_f32_e32 v80, v223, v87
	v_cvt_pk_bf16_f32 v80, v80, s0
	buffer_store_short v80, v175, s[8:11], s62 offen
.LBB0_2239:
	s_mov_b32 s98, -1
	s_andn2_b64 vcc, exec, s[6:7]
	s_mov_b32 s91, s86
	s_cbranch_vccnz .LBB0_2244
	s_lshl_b32 s89, s88, 5
	s_cmp_gt_u32 s88, 7
	s_mov_b64 s[8:9], -1
	s_cbranch_scc0 .LBB0_2242
	s_sub_i32 s91, 0x11e0, s89
	s_mov_b64 s[8:9], 0

; #define MFMA32(a, b, c) __builtin_amdgcn_mfma_f32_32x32x16_bf16((a), (b), (c), 0, 0, 0)
; #define PACK16(x, s2) pack8(x[8 * (s2)], x[8 * (s2) + 1], x[8 * (s2) + 2], x[8 * (s2) + 3], x[8 * (s2) + 4], x[8 * (s2) + 5], x[8 * (s2) + 6], x[8 * (s2) + 7])
; DI void scan_item(const P& p, char* shm, int item) {
;     ...
;         if (p0 >= CTXL) {
;             f32x16 pT;
; #pragma unroll
;             for (int r = 0; r < 16; ++r) pT[r] = 0.f;
; #pragma unroll
;             for (int s8 = 0; s8 < 8; ++s8) {
;                 const unsigned o = Lrd ^ (32u * s8);
;                 const bf16x8 a = *(const bf16x8*)(kimg + o);
;                 const bf16x8 bq = *(const bf16x8*)(qimg + 8 * hh + 32 * s8);
;                 pT = MFMA32(a, bq, pT);
;             }
; #pragma unroll
;             for (int r = 0; r < 16; ++r) pT[r] *= dmask[r];
;             bf16x8 pfr[2];
;             pfr[0] = PACK16(pT, 0);
;             pfr[1] = PACK16(pT, 1);
;             f32x16 o;
; #pragma unroll
;             for (int r = 0; r < 16; ++r) o[r] = 0.f;
; #pragma unroll
;             for (int db = 0; db < 4; ++db)
; #pragma unroll
;                 for (int s2 = 0; s2 < 2; ++s2) {
;                     const bf16x8 bfrag = PACK16(st[db], s2);
;                     const s16x4 qlo = *(const s16x4*)(qimg + db * 64 + 32 * s2), qhi = *(const s16x4*)(qimg + db * 64 + 32 * s2 + 16);
;                     const bf16x8 a2 = __builtin_shufflevector(qlo, qhi, 0, 1, 2, 3, 4, 5, 6, 7);
;                     o = MFMA32(a2, bfrag, o);
;                 }
; #pragma unroll
;             for (int r = 0; r < 16; ++r) o[r] *= qlane * __builtin_amdgcn_exp2f(lgs * (float)((r & 3) + 8 * (r >> 2)));
; #pragma unroll
;             for (int s2 = 0; s2 < 2; ++s2) {
;                 const char* vp = buf + SC_V + vrow + 8 * hh + 32 * s2;
;                 const s16x4 vlo = *(const s16x4*)vp, vhi = *(const s16x4*)(vp + 16);
;                 const bf16x8 b3 = __builtin_shufflevector(vlo, vhi, 0, 1, 2, 3, 4, 5, 6, 7);
;                 o = MFMA32(pfr[s2], b3, o);
;             }
.LBB0_2244:
	s_and_b32 s92, s88, 1
	s_mul_i32 s8, s92, 0xd200
	s_add_i32 s90, s8, 16
	s_add_i32 s89, s90, s85
	s_cmpk_lt_u32 s91, 0x100
	s_cbranch_scc1 .LBB0_2251
	s_add_i32 s8, s90, s83
	v_add_u32_e32 v196, s8, v177
	v_add_u32_e32 v102, v196, v166
	v_add_u32_e32 v97, s89, v188
	ds_read_b128 v[224:227], v97 offset:16896
	ds_read_b128 v[228:231], v102
	v_xad_u32 v97, v188, 32, s89
	ds_read_b128 v[232:235], v97 offset:16896
	ds_read_b128 v[236:239], v102 offset:32
	v_xad_u32 v97, v188, 64, s89
	ds_read_b128 v[240:243], v97 offset:16896
	ds_read_b128 v[244:247], v102 offset:64
	ds_read2_b64 v[248:251], v196 offset1:2
	ds_read2_b64 v[198:201], v196 offset0:4 offset1:6
	v_cvt_pk_bf16_f32 v202, v64, v65
	v_cvt_pk_bf16_f32 v203, v66, v67
	v_cvt_pk_bf16_f32 v204, v68, v69
	v_cvt_pk_bf16_f32 v205, v70, v71
	v_xor_b32_e32 v97, 0x60, v188
	v_add_u32_e32 v97, s89, v97
	s_waitcnt lgkmcnt(6)
	v_mfma_f32_32x32x16_bf16 v[80:95], v[224:227], v[228:231], 0
	ds_read_b128 v[224:227], v97 offset:16896
	ds_read_b128 v[228:231], v102 offset:96
	v_xor_b32_e32 v97, 0x80, v188
	v_add_u32_e32 v97, s89, v97
	s_waitcnt lgkmcnt(6)
	v_mfma_f32_32x32x16_bf16 v[80:95], v[232:235], v[236:239], v[80:95]
	ds_read_b128 v[232:235], v97 offset:16896
	ds_read_b128 v[236:239], v102 offset:128
	v_xor_b32_e32 v97, 0xa0, v188
	v_add_u32_e32 v97, s89, v97
	s_waitcnt lgkmcnt(6)
	v_mfma_f32_32x32x16_bf16 v[80:95], v[240:243], v[244:247], v[80:95]
	ds_read_b128 v[240:243], v97 offset:16896
	ds_read_b128 v[244:247], v102 offset:160
	s_waitcnt lgkmcnt(7)
	v_mfma_f32_32x32x16_bf16 v[208:223], v[248:251], v[202:205], 0
	ds_read2_b64 v[248:251], v196 offset0:8 offset1:10
	v_cvt_pk_bf16_f32 v98, v72, v73
	v_cvt_pk_bf16_f32 v99, v74, v75
	v_cvt_pk_bf16_f32 v100, v76, v77
	v_cvt_pk_bf16_f32 v101, v78, v79
	v_xor_b32_e32 v97, 0xc0, v188
	v_add_u32_e32 v97, s89, v97
	s_waitcnt lgkmcnt(5)
	v_mfma_f32_32x32x16_bf16 v[80:95], v[224:227], v[228:231], v[80:95]
	ds_read_b128 v[224:227], v97 offset:16896
	ds_read_b128 v[228:231], v102 offset:192
	v_mfma_f32_32x32x16_bf16 v[208:223], v[198:201], v[98:101], v[208:223]
	ds_read2_b64 v[198:201], v196 offset0:12 offset1:14
	v_cvt_pk_bf16_f32 v202, v48, v49
	v_cvt_pk_bf16_f32 v203, v50, v51
	v_cvt_pk_bf16_f32 v204, v52, v53
	v_cvt_pk_bf16_f32 v205, v54, v55
	v_xor_b32_e32 v97, 0xe0, v188
	v_add_u32_e32 v97, s89, v97
	s_waitcnt lgkmcnt(6)
	v_mfma_f32_32x32x16_bf16 v[80:95], v[232:235], v[236:239], v[80:95]
	ds_read_b128 v[232:235], v97 offset:16896
	ds_read_b128 v[236:239], v102 offset:224
	s_waitcnt lgkmcnt(5)
	v_mfma_f32_32x32x16_bf16 v[208:223], v[248:251], v[202:205], v[208:223]
	ds_read2_b64 v[248:251], v196 offset0:16 offset1:18
	v_cvt_pk_bf16_f32 v98, v56, v57
	v_cvt_pk_bf16_f32 v99, v58, v59
	v_cvt_pk_bf16_f32 v100, v60, v61
	v_cvt_pk_bf16_f32 v101, v62, v63
	v_add3_u32 v97, s90, v167, v166
	v_add_u32_e32 v97, 0x8000, v97
	v_mfma_f32_32x32x16_bf16 v[80:95], v[240:243], v[244:247], v[80:95]
	ds_read2_b64 v[240:243], v97 offset0:64 offset1:66
	ds_read2_b64 v[244:247], v97 offset0:68 offset1:70
	s_waitcnt lgkmcnt(5)
	v_mfma_f32_32x32x16_bf16 v[208:223], v[198:201], v[98:101], v[208:223]
	ds_read2_b64 v[198:201], v196 offset0:20 offset1:22
	v_cvt_pk_bf16_f32 v202, v32, v33
	v_cvt_pk_bf16_f32 v203, v34, v35
	v_cvt_pk_bf16_f32 v204, v36, v37
	v_cvt_pk_bf16_f32 v205, v38, v39
	v_mfma_f32_32x32x16_bf16 v[80:95], v[224:227], v[228:231], v[80:95]
	s_waitcnt lgkmcnt(3)
	v_mfma_f32_32x32x16_bf16 v[208:223], v[248:251], v[202:205], v[208:223]
	ds_read2_b64 v[248:251], v196 offset0:24 offset1:26
	v_cvt_pk_bf16_f32 v98, v40, v41
	v_cvt_pk_bf16_f32 v99, v42, v43
	v_cvt_pk_bf16_f32 v100, v44, v45
	v_cvt_pk_bf16_f32 v101, v46, v47
	v_mfma_f32_32x32x16_bf16 v[80:95], v[232:235], v[236:239], v[80:95]
	s_waitcnt lgkmcnt(1)
	v_mfma_f32_32x32x16_bf16 v[208:223], v[198:201], v[98:101], v[208:223]
	v_cvt_pk_bf16_f32 v202, v16, v17
	v_cvt_pk_bf16_f32 v203, v18, v19
	v_cvt_pk_bf16_f32 v204, v20, v21
	v_cvt_pk_bf16_f32 v205, v22, v23
	ds_read2_b64 v[198:201], v196 offset0:28 offset1:30
	s_waitcnt lgkmcnt(1)
	v_mfma_f32_32x32x16_bf16 v[208:223], v[248:251], v[202:205], v[208:223]
	v_cvt_pk_bf16_f32 v98, v24, v25
	v_cvt_pk_bf16_f32 v99, v26, v27
	v_cvt_pk_bf16_f32 v100, v28, v29
	v_cvt_pk_bf16_f32 v101, v30, v31
	v_mul_f32_e32 v80, v168, v80
	v_mul_f32_e32 v81, v169, v81
	v_mul_f32_e32 v82, v170, v82
	v_mul_f32_e32 v83, v171, v83
	s_waitcnt lgkmcnt(0)
	v_mfma_f32_32x32x16_bf16 v[208:223], v[198:201], v[98:101], v[208:223]
	v_mul_f32_e32 v84, v172, v84
	v_mul_f32_e32 v85, v173, v85
	v_mul_f32_e32 v86, v174, v86
	v_mul_f32_e32 v87, v176, v87
	v_mul_f32_e32 v88, v182, v88
	v_mul_f32_e32 v89, v183, v89
	v_mul_f32_e32 v90, v186, v90
	v_mul_f32_e32 v91, v184, v91
	v_mul_f32_e32 v92, v185, v92
	v_mul_f32_e32 v93, v180, v93
	v_mul_f32_e32 v94, v181, v94
	v_mul_f32_e32 v95, v179, v95
	v_cvt_pk_bf16_f32 v96, v80, v81
	v_cvt_pk_bf16_f32 v97, v82, v83
	v_cvt_pk_bf16_f32 v98, v84, v85
	v_cvt_pk_bf16_f32 v99, v86, v87
	v_cvt_pk_bf16_f32 v100, v88, v89
	v_cvt_pk_bf16_f32 v101, v90, v91
	v_cvt_pk_bf16_f32 v102, v92, v93
	v_cvt_pk_bf16_f32 v103, v94, v95
	v_pk_mul_f32 v[208:209], v[134:135], v[208:209]
	v_pk_mul_f32 v[210:211], v[136:137], v[210:211]
	v_pk_mul_f32 v[212:213], v[138:139], v[212:213]
	v_pk_mul_f32 v[214:215], v[140:141], v[214:215]
	v_pk_mul_f32 v[216:217], v[142:143], v[216:217]
	v_pk_mul_f32 v[218:219], v[144:145], v[218:219]
	v_pk_mul_f32 v[220:221], v[146:147], v[220:221]
	v_pk_mul_f32 v[222:223], v[148:149], v[222:223]
	s_nop 1
	v_mfma_f32_32x32x16_bf16 v[208:223], v[96:99], v[240:243], v[208:223]
	v_mfma_f32_32x32x16_bf16 v[208:223], v[100:103], v[244:247], v[208:223]
	s_mov_b64 s[8:9], -1
	s_and_b64 vcc, exec, s[36:37]
	s_cbranch_vccz .LBB0_2247
	s_add_i32 s93, s91, 0xffffff00
	s_mov_b64 s[8:9], 0

; DI float bf2f(unsigned short b) { return __uint_as_float(((unsigned)b) << 16); }
; DI void scan_item(const P& p, char* shm, int item) {
;     ...
;         *(bf16x8*)(buf + SC_V + ldsV) = vv;
;         float f[8];
; #pragma unroll
;         for (int e = 0; e < 8; ++e) {
;             const int j = (tid & 3) * 8 + e;
;             f[e] = bf2f((unsigned short)vv[e]) * __builtin_amdgcn_exp2f(lg2 * (float)(dir == 0 ? 31 - j : j));
;         }
;         *(bf16x8*)(buf + SC_VS + ldsV) = pack8(f[0], f[1], f[2], f[3], f[4], f[5], f[6], f[7]);
;     ...
;         if (s + 1 < nsteps) store_chunk(s + 1);
;         if (s + 2 < nsteps) issue_chunk(s + 2);
.LBB0_2261:
	s_waitcnt vmcnt(0)
	v_and_b32_e32 v81, 0xffff0000, v116
	v_lshlrev_b32_e32 v80, 16, v116
	v_and_b32_e32 v83, 0xffff0000, v117
	v_lshlrev_b32_e32 v82, 16, v117
	v_and_b32_e32 v85, 0xffff0000, v118
	v_lshlrev_b32_e32 v84, 16, v118
	v_and_b32_e32 v87, 0xffff0000, v119
	v_lshlrev_b32_e32 v86, 16, v119
	v_pk_mul_f32 v[80:81], v[154:155], v[80:81]
	v_pk_mul_f32 v[82:83], v[156:157], v[82:83]
	v_pk_mul_f32 v[84:85], v[158:159], v[84:85]
	v_pk_mul_f32 v[86:87], v[160:161], v[86:87]
	v_add_u32_e32 v88, s8, v104
	v_cvt_pk_bf16_f32 v80, v80, v81
	v_cvt_pk_bf16_f32 v81, v82, v83
	v_cvt_pk_bf16_f32 v82, v84, v85
	v_cvt_pk_bf16_f32 v83, v86, v87
	ds_write_b128 v88, v[116:119] offset:33280
	ds_write_b128 v88, v[80:83] offset:43520
	s_mov_b64 s[8:9], -1
	s_and_b64 vcc, exec, s[6:7]
	s_cbranch_vccz .LBB0_2267
	s_lshl_b32 s93, s88, 5
	s_add_i32 s93, s93, 64
	s_cmp_gt_u32 s88, 5
	s_cbranch_scc0 .LBB0_2264
	s_sub_i32 s92, 0x11e0, s93
	s_mov_b64 s[8:9], 0

; #define MFMA32(a, b, c) __builtin_amdgcn_mfma_f32_32x32x16_bf16((a), (b), (c), 0, 0, 0)
; DI void scan_item(const P& p, char* shm, int item) {
;     ...
;         {
;             const unsigned ka = (unsigned)(size_t)kimg;
;             const char* vsp = buf + SC_VS + vrow + 16 * hh;
;             const bf16x8 bv0 = *(const bf16x8*)(vsp), bv1 = *(const bf16x8*)(vsp + 32);
;             s16x4 tr[2][4];
;             tr_issue4(tr[0], ka + Ltr, ka + 1024u + (Ltr ^ 16u), ka + 4096u + Ltr, ka + 5120u + (Ltr ^ 16u));
; #pragma unroll
;             for (int db = 0; db < 4; ++db) {
;                 if (db < 3) {
;                     const unsigned cx = 64u * (db + 1);
;                     tr_issue4(tr[(db + 1) & 1], ka + (Ltr ^ cx), ka + 1024u + (Ltr ^ (cx + 16u)), ka + 4096u + (Ltr ^ cx), ka + 5120u + (Ltr ^ (cx + 16u)));
;                     tr_wait4<4>(tr[db & 1]);
;                 } else {
;                     tr_wait4<0>(tr[db & 1]);
;                 }
;                 st[db] *= cdec;
; #pragma unroll
;                 for (int ks = 0; ks < 2; ++ks) {
;                     const bf16x8 a = __builtin_shufflevector(tr[db & 1][2 * ks], tr[db & 1][2 * ks + 1], 0, 1, 2, 3, 4, 5, 6, 7);
;                     st[db] = MFMA32(a, ks ? bv1 : bv0, st[db]);
;                 }
;             }
;         }
;         __syncthreads();
;     }
;     if (dh == 0 && pprev >= 0) flush_prev(nsteps - 1);
.LBB0_2271:
	s_ashr_i32 s8, s92, 5
	s_add_i32 s88, s89, 0x4200
	s_ashr_i32 s9, s8, 31
	s_add_u32 s8, s82, s8
	s_addc_u32 s9, s79, s9
	s_lshl_b64 s[8:9], s[8:9], 18
	s_or_b64 s[8:9], s[8:9], s[38:39]
	v_lshl_add_u64 v[80:81], v[108:109], 0, s[8:9]
	global_load_dwordx4 v[116:119], v[80:81], off
	v_add3_u32 v84, s90, v167, v189
	v_add_u32_e32 v96, s88, v133
	s_add_i32 s8, s89, 0x4600
	v_xor_b32_e32 v88, 16, v133
	s_add_i32 s9, s89, 0x5200
	s_addk_i32 s89, 0x5600
	ds_read_b128 v[80:83], v84 offset:43520
	ds_read_b128 v[84:87], v84 offset:43552
	v_add_u32_e32 v97, s8, v88
	v_add_u32_e32 v98, s9, v133
	v_add_u32_e32 v99, s89, v88
	ds_read_b64_tr_b16 v[92:93], v96
	ds_read_b64_tr_b16 v[94:95], v97
	ds_read_b64_tr_b16 v[88:89], v98
	ds_read_b64_tr_b16 v[90:91], v99
	v_xor_b32_e32 v96, 64, v133
	v_add_u32_e32 v151, s88, v96
	v_xor_b32_e32 v97, 0x50, v133
	v_add_u32_e32 v196, s8, v97
	v_add_u32_e32 v197, s9, v96
	v_add_u32_e32 v198, s89, v97
	ds_read_b64_tr_b16 v[100:101], v151
	ds_read_b64_tr_b16 v[102:103], v196
	ds_read_b64_tr_b16 v[96:97], v197
	ds_read_b64_tr_b16 v[98:99], v198
	v_mov_b32_e32 v151, v150
	v_pk_mul_f32 v[78:79], v[150:151], v[78:79]
	v_pk_mul_f32 v[76:77], v[150:151], v[76:77]
	v_pk_mul_f32 v[74:75], v[150:151], v[74:75]
	v_pk_mul_f32 v[72:73], v[150:151], v[72:73]
	v_pk_mul_f32 v[70:71], v[150:151], v[70:71]
	v_pk_mul_f32 v[68:69], v[150:151], v[68:69]
	v_pk_mul_f32 v[66:67], v[150:151], v[66:67]
	v_pk_mul_f32 v[64:65], v[152:153], v[64:65]
	s_waitcnt lgkmcnt(4)
	v_pk_mul_f32 v[62:63], v[150:151], v[62:63]
	v_pk_mul_f32 v[60:61], v[150:151], v[60:61]
	s_waitcnt lgkmcnt(1)
	v_mfma_f32_32x32x16_bf16 v[64:79], v[92:95], v[80:83], v[64:79]
	v_pk_mul_f32 v[58:59], v[150:151], v[58:59]
	v_pk_mul_f32 v[56:57], v[150:151], v[56:57]
	v_pk_mul_f32 v[54:55], v[150:151], v[54:55]
	v_pk_mul_f32 v[52:53], v[150:151], v[52:53]
	v_pk_mul_f32 v[50:51], v[150:151], v[50:51]
	v_pk_mul_f32 v[48:49], v[152:153], v[48:49]
	v_pk_mul_f32 v[46:47], v[150:151], v[46:47]
	s_waitcnt lgkmcnt(0)
	v_mfma_f32_32x32x16_bf16 v[64:79], v[88:91], v[84:87], v[64:79]
	v_xor_b32_e32 v88, 0x80, v133
	v_xor_b32_e32 v89, 0x90, v133
	v_add_u32_e32 v196, s88, v88
	v_add_u32_e32 v197, s8, v89
	v_add_u32_e32 v198, s9, v88
	v_add_u32_e32 v199, s89, v89
	ds_read_b64_tr_b16 v[92:93], v196
	ds_read_b64_tr_b16 v[94:95], v197
	ds_read_b64_tr_b16 v[88:89], v198
	ds_read_b64_tr_b16 v[90:91], v199
	s_waitcnt lgkmcnt(4)
	v_pk_mul_f32 v[44:45], v[150:151], v[44:45]
	v_mfma_f32_32x32x16_bf16 v[48:63], v[100:103], v[80:83], v[48:63]
	v_pk_mul_f32 v[42:43], v[150:151], v[42:43]
	v_pk_mul_f32 v[40:41], v[150:151], v[40:41]
	v_pk_mul_f32 v[38:39], v[150:151], v[38:39]
	v_pk_mul_f32 v[36:37], v[150:151], v[36:37]
	v_pk_mul_f32 v[34:35], v[150:151], v[34:35]
	v_pk_mul_f32 v[32:33], v[152:153], v[32:33]
	v_pk_mul_f32 v[30:31], v[150:151], v[30:31]
	v_mfma_f32_32x32x16_bf16 v[48:63], v[96:99], v[84:87], v[48:63]
	v_xor_b32_e32 v96, 0xc0, v133
	v_xor_b32_e32 v97, 0xd0, v133
	v_add_u32_e32 v196, s88, v96
	v_add_u32_e32 v105, s8, v97
	v_add_u32_e32 v197, s9, v96
	v_add_u32_e32 v198, s89, v97
	ds_read_b64_tr_b16 v[100:101], v196
	ds_read_b64_tr_b16 v[102:103], v105
	ds_read_b64_tr_b16 v[96:97], v197
	ds_read_b64_tr_b16 v[98:99], v198
	s_waitcnt lgkmcnt(4)
	v_pk_mul_f32 v[28:29], v[150:151], v[28:29]
	v_pk_mul_f32 v[26:27], v[150:151], v[26:27]
	v_pk_mul_f32 v[24:25], v[150:151], v[24:25]
	v_pk_mul_f32 v[22:23], v[150:151], v[22:23]
	v_pk_mul_f32 v[20:21], v[150:151], v[20:21]
	v_pk_mul_f32 v[18:19], v[150:151], v[18:19]
	v_pk_mul_f32 v[16:17], v[152:153], v[16:17]
	v_mfma_f32_32x32x16_bf16 v[32:47], v[92:95], v[80:83], v[32:47]
	s_waitcnt lgkmcnt(0)
	s_addk_i32 s87, 0x4000
	s_add_i32 s86, s86, 32
	s_cmpk_eq_i32 s91, 0x86
	s_barrier
	v_mfma_f32_32x32x16_bf16 v[16:31], v[100:103], v[80:83], v[16:31]
	v_mfma_f32_32x32x16_bf16 v[32:47], v[88:91], v[84:87], v[32:47]
	v_mfma_f32_32x32x16_bf16 v[16:31], v[96:99], v[84:87], v[16:31]
	s_cbranch_scc1 .LBB0_2273
	s_mov_b32 s88, s91
	s_branch .LBB0_2237
.LBB0_2273:
	s_mov_b32 s14, -1
	s_cmp_gt_i32 s98, -1
	s_cbranch_scc0 .Lscan_tail_nocommit
	v_mov_b64_e32 v[0:1], v[208:209]
	v_mov_b64_e32 v[2:3], v[210:211]
	v_mov_b64_e32 v[4:5], v[212:213]
	v_mov_b64_e32 v[6:7], v[214:215]
	v_mov_b64_e32 v[8:9], v[216:217]
	v_mov_b64_e32 v[10:11], v[218:219]
	v_mov_b64_e32 v[12:13], v[220:221]
	v_mov_b64_e32 v[14:15], v[222:223]
	s_mov_b32 s14, s98
